# speedup vs baseline: 1.0568x; 1.0242x over previous
; __device__ __forceinline__ void expSM(f32x16& p1) { for (int r = 0; r < 16; ++r) p1[r] = __builtin_amdgcn_exp2f(p1[r]); }
; #define KDMA(t, b) do { const int so_ = (t) * (int)SHM_K; LAS unsigned char* d_ = kdst + (b) * (int)SHM_K; \
;     __builtin_amdgcn_raw_ptr_buffer_load_lds(rsK, (LAS void*)d_, 16, kg0, so_, 0, 0); __builtin_amdgcn_raw_ptr_buffer_load_lds(rsK, (LAS void*)(d_ + 1024), 16, kg1, so_, 0, 0); } while (0)
; #define RESC(a) do { if (__any((a) < 1.f)) { if (hi == 0) al_l[r32] = (a); asm volatile("s_waitcnt lgkmcnt(0)" ::: "memory"); \
;     for (int d = 0; d < 8; ++d) for (int r = 0; r < 16; ++r) o[d][r] *= al_l[crow(r, hi)]; } } while (0)
; __device__ __forceinline__ void partialSM(f32x16& p0, f32x16& p1, f32x16& nm, bool first, float& alpha) {
;     ...
;     for (int r = 0; r < 16; ++r) p0[r] = __builtin_amdgcn_exp2f(p0[r]);
; }
; __device__ __forceinline__ void finishSM(f32x16& p0, f32x16& p1, float alpha, float& l_reg, bf16x8& pa0, bf16x8& pa1, bf16x8& pa2, bf16x8& pa3) {
;     float ps = 0; for (int r = 0; r < 16; ++r) ps += p0[r]; for (int r = 0; r < 16; ++r) ps += p1[r];
;     { auto rr = __builtin_amdgcn_permlane32_swap(__float_as_uint(ps), __float_as_uint(ps), false, false);
;       ps = __uint_as_float(rr[0]) + __uint_as_float(rr[1]); }
;     l_reg = l_reg * alpha + ps;
;     ...
;     PK4(p0, 0, pa0); PK4(p0, 8, pa1); PK4(p1, 0, pa2); PK4(p1, 8, pa3);
;     ...
; }
; __device__ __forceinline__ void attn_dense_body(const bf16_t* __restrict__ Qb, const bf16_t* __restrict__ Kh, const bf16_t* __restrict__ Vh,
;                                                 float* __restrict__ Ob, int seq, char* lds, LAS unsigned char* lds3, const int tid) {
;     ...
;     for (int j = 0; j < NT; ++j) {
;         { const int tk = j + 2 < NT ? j + 2 : NT - 1, tv = j + 1 < NT ? j + 1 : NT - 1; KDMA(tk, b2); VDMA(tv, b1); }
;         partialSM(p0, p1, nm, j == 0, al);
;         expSM(p1);
;         finishSM(p0, p1, al, l_reg, pa0, pa1, pa2, pa3);
;         RESC(al);
;         const int vb = vb0 + b * (int)SHM_V;
.Lat_loop:
	s_add_i32 s18, s89, 2
	s_lshl_b32 s26, s10, 14
	s_min_u32 s18, s18, s67
	s_add_i32 s26, s96, s26
	s_lshl_b32 s18, s18, 14
	s_mov_b32 m0, s26
	s_mov_b32 s1, s89
	buffer_load_dwordx4 v240, s[28:31], s18 offen lds
	s_add_i32 m0, s26, 0x400
	s_add_i32 s89, s89, 1
	buffer_load_dwordx4 v241, s[28:31], s18 offen lds
	s_lshl_b32 s18, s99, 15
	s_min_u32 s19, s89, s67
	s_add_i32 s27, s98, s18
	s_lshl_b32 s26, s19, 15
	s_mov_b32 s18, s30
	s_mov_b32 s19, s31
	s_mov_b32 m0, s27
	s_or_b32 s84, s26, 0x80
	buffer_load_dwordx4 v242, s[16:19], s26 offen lds
	s_add_i32 m0, s27, 0x400
	s_nop 0
	buffer_load_dwordx4 v242, s[16:19], s84 offen lds
	s_add_i32 m0, s27, 0x800
	s_or_b32 s84, s26, 0x100
	buffer_load_dwordx4 v242, s[16:19], s84 offen lds
	s_add_i32 m0, s27, 0xc00
	s_or_b32 s26, s26, 0x180
	buffer_load_dwordx4 v242, s[16:19], s26 offen lds
	s_mov_b32 s91, s0
	s_mov_b32 s84, 0
	s_cmp_lg_u32 s1, 0
	s_cbranch_scc0 .Lat_resc
.Lat_exp:
	v_exp_f32_e32 v160, v160
	v_exp_f32_e32 v164, v164
	v_exp_f32_e32 v161, v161
	v_exp_f32_e32 v165, v165
	v_exp_f32_e32 v162, v162
	v_exp_f32_e32 v166, v166
	v_add_f32_e32 v0, v160, v161
	v_add_f32_e32 v14, v164, v165
	v_exp_f32_e32 v163, v163
	v_exp_f32_e32 v167, v167
	v_add_f32_e32 v0, v0, v162
	v_add_f32_e32 v14, v14, v166
	v_exp_f32_e32 v168, v168
	v_exp_f32_e32 v172, v172
	v_add_f32_e32 v0, v0, v163
	v_add_f32_e32 v14, v14, v167
	v_exp_f32_e32 v169, v169
	v_exp_f32_e32 v173, v173
	v_add_f32_e32 v0, v0, v168
	v_add_f32_e32 v14, v14, v172
	v_exp_f32_e32 v170, v170
	v_exp_f32_e32 v174, v174
	v_add_f32_e32 v0, v0, v169
	v_add_f32_e32 v14, v14, v173
	v_exp_f32_e32 v171, v171
	v_exp_f32_e32 v175, v175
	v_add_f32_e32 v0, v0, v170
	v_add_f32_e32 v14, v14, v174
	v_exp_f32_e32 v176, v176
	v_exp_f32_e32 v180, v180
	v_add_f32_e32 v0, v0, v171
	v_add_f32_e32 v14, v14, v175
	v_exp_f32_e32 v177, v177
	v_exp_f32_e32 v181, v181
	v_add_f32_e32 v0, v0, v176
	v_add_f32_e32 v14, v14, v180
	v_exp_f32_e32 v178, v178
	v_exp_f32_e32 v182, v182
	v_add_f32_e32 v0, v0, v177
	v_add_f32_e32 v14, v14, v181
	v_exp_f32_e32 v179, v179
	v_exp_f32_e32 v183, v183
	v_add_f32_e32 v0, v0, v178
	v_add_f32_e32 v14, v14, v182
	v_exp_f32_e32 v184, v184
	v_exp_f32_e32 v188, v188
	v_add_f32_e32 v0, v0, v179
	v_add_f32_e32 v14, v14, v183
	v_exp_f32_e32 v185, v185
	v_exp_f32_e32 v189, v189
	v_add_f32_e32 v0, v0, v184
	v_add_f32_e32 v14, v14, v188
	v_exp_f32_e32 v186, v186
	v_exp_f32_e32 v190, v190
	v_add_f32_e32 v0, v0, v185
	v_add_f32_e32 v14, v14, v189
	v_exp_f32_e32 v187, v187
	v_exp_f32_e32 v191, v191
	v_add_f32_e32 v0, v0, v186
	v_add_f32_e32 v14, v14, v190
	v_add_f32_e32 v0, v0, v187
	v_add_f32_e32 v14, v14, v191
	s_cmp_lg_u32 s84, 0
	s_cbranch_scc1 .Lat_cont
	v_max_f32_e32 v15, v0, v14
	s_mov_b32 s0, 0x453a5000
	v_cmp_ge_f32_e32 vcc, s0, v15
	s_cmp_lg_u64 vcc, exec
	s_cbranch_scc1 .Lat_redo
.Lat_cont:
	v_add_f32_e32 v245, v245, v0
	v_add_f32_e32 v229, v229, v14
	v_cvt_pk_bf16_f32 v2, v160, v161
	v_cvt_pk_bf16_f32 v3, v162, v163
	v_cvt_pk_bf16_f32 v4, v168, v169
	v_cvt_pk_bf16_f32 v5, v170, v171
	v_cvt_pk_bf16_f32 v6, v176, v177
	v_cvt_pk_bf16_f32 v7, v178, v179
	v_cvt_pk_bf16_f32 v8, v184, v185
	v_cvt_pk_bf16_f32 v9, v186, v187
	v_cvt_pk_bf16_f32 v10, v164, v165
	v_cvt_pk_bf16_f32 v11, v166, v167
	v_cvt_pk_bf16_f32 v12, v172, v173
	v_cvt_pk_bf16_f32 v13, v174, v175
	v_cvt_pk_bf16_f32 v152, v180, v181
	v_cvt_pk_bf16_f32 v153, v182, v183
	v_cvt_pk_bf16_f32 v154, v188, v189
	v_cvt_pk_bf16_f32 v155, v190, v191
	v_lshl_add_u32 v14, s91, 15, v247
	v_lshl_add_u32 v232, s99, 14, v246
	v_add_u32_e32 v0, v239, v232
	v_xad_u32 v15, v239, 64, v232
	v_xad_u32 v231, v239, s60, v232
	s_movk_i32 s0, 0xc0
	v_xad_u32 v232, v239, s0, v232
	ds_read_b64_tr_b16 v[160:161], v14 offset:0
	ds_read_b64_tr_b16 v[162:163], v14 offset:8192
	ds_read_b64_tr_b16 v[164:165], v14 offset:256
	ds_read_b64_tr_b16 v[166:167], v14 offset:8448
	ds_read_b64_tr_b16 v[168:169], v14 offset:512
	ds_read_b64_tr_b16 v[170:171], v14 offset:8704
	ds_read_b64_tr_b16 v[172:173], v14 offset:768
	ds_read_b64_tr_b16 v[174:175], v14 offset:8960
	ds_read_b64_tr_b16 v[176:177], v14 offset:1024
	ds_read_b64_tr_b16 v[178:179], v14 offset:9216
	ds_read_b64_tr_b16 v[180:181], v14 offset:1280
	ds_read_b64_tr_b16 v[182:183], v14 offset:9472
	ds_read_b64_tr_b16 v[184:185], v14 offset:1536
	ds_read_b64_tr_b16 v[186:187], v14 offset:9728
	ds_read_b64_tr_b16 v[188:189], v14 offset:1792
	ds_read_b64_tr_b16 v[190:191], v14 offset:9984
	s_waitcnt vmcnt(6) lgkmcnt(0)
	s_barrier
; #define RD2(S, k, D0) do { S##l##k = tr_read<v_rd_off(D0, k, 0)>(vb); S##h##k = tr_read<v_rd_off(D0, k, 1)>(vb); } while (0)
; #define PVB(X, Y, D0, D1) do { LW(6); MF(X, 0, D0, pa0); SBAR(); RD2(Y, 0, D1); LW(6); MF(X, 1, D0, pa1); SBAR(); RD2(Y, 1, D1); \
;     LW(6); MF(X, 2, D0, pa2); SBAR(); RD2(Y, 2, D1); LW(6); MF(X, 3, D0, pa3); SBAR(); RD2(Y, 3, D1); } while (0)
; __device__ __forceinline__ void attn_dense_body(const bf16_t* __restrict__ Qb, const bf16_t* __restrict__ Kh, const bf16_t* __restrict__ Vh,
;                                                 float* __restrict__ Ob, int seq, char* lds, LAS unsigned char* lds3, const int tid) {
;     ...
;           __builtin_amdgcn_s_setprio(1);
;           RD2(A, 0, 0); RD2(A, 1, 0); RD2(A, 2, 0); RD2(A, 3, 0);
;           PVB(A, B, 0, 1); PVB(B, A, 1, 2); PVB(A, B, 2, 3); PVB(B, A, 3, 4); PVB(A, B, 4, 5); PVB(B, A, 5, 6); PVB(A, B, 6, 7);
	s_setprio 1
	v_mfma_f32_16x16x32_bf16 v[16:19], v[2:5], v[160:163], v[16:19]
	v_mfma_f32_16x16x32_bf16 v[80:83], v[10:13], v[160:163], v[80:83]
	v_mfma_f32_16x16x32_bf16 v[20:23], v[2:5], v[164:167], v[20:23]
	ds_read_b64_tr_b16 v[160:161], v14 offset:16384
	v_mfma_f32_16x16x32_bf16 v[84:87], v[10:13], v[164:167], v[84:87]
	ds_read_b64_tr_b16 v[162:163], v14 offset:24576
	v_mfma_f32_16x16x32_bf16 v[24:27], v[2:5], v[168:171], v[24:27]
	ds_read_b64_tr_b16 v[164:165], v14 offset:16640
	v_mfma_f32_16x16x32_bf16 v[88:91], v[10:13], v[168:171], v[88:91]
	ds_read_b64_tr_b16 v[166:167], v14 offset:24832
	v_mfma_f32_16x16x32_bf16 v[28:31], v[2:5], v[172:175], v[28:31]
	ds_read_b64_tr_b16 v[168:169], v14 offset:16896
	v_mfma_f32_16x16x32_bf16 v[92:95], v[10:13], v[172:175], v[92:95]
	ds_read_b64_tr_b16 v[170:171], v14 offset:25088
	v_mfma_f32_16x16x32_bf16 v[32:35], v[2:5], v[176:179], v[32:35]
	ds_read_b64_tr_b16 v[172:173], v14 offset:17152
	v_mfma_f32_16x16x32_bf16 v[96:99], v[10:13], v[176:179], v[96:99]
	ds_read_b64_tr_b16 v[174:175], v14 offset:25344
	v_mfma_f32_16x16x32_bf16 v[36:39], v[2:5], v[180:183], v[36:39]
	ds_read_b64_tr_b16 v[176:177], v14 offset:17408
	v_mfma_f32_16x16x32_bf16 v[100:103], v[10:13], v[180:183], v[100:103]
	ds_read_b64_tr_b16 v[178:179], v14 offset:25600
	v_mfma_f32_16x16x32_bf16 v[40:43], v[2:5], v[184:187], v[40:43]
	ds_read_b64_tr_b16 v[180:181], v14 offset:17664
	v_mfma_f32_16x16x32_bf16 v[104:107], v[10:13], v[184:187], v[104:107]
	ds_read_b64_tr_b16 v[182:183], v14 offset:25856
	v_mfma_f32_16x16x32_bf16 v[44:47], v[2:5], v[188:191], v[44:47]
	ds_read_b64_tr_b16 v[184:185], v14 offset:17920
	v_mfma_f32_16x16x32_bf16 v[108:111], v[10:13], v[188:191], v[108:111]
	ds_read_b64_tr_b16 v[186:187], v14 offset:26112
	s_waitcnt lgkmcnt(10)
	v_mfma_f32_16x16x32_bf16 v[16:19], v[6:9], v[160:163], v[16:19]
	ds_read_b64_tr_b16 v[188:189], v14 offset:18176
	v_mfma_f32_16x16x32_bf16 v[80:83], v[152:155], v[160:163], v[80:83]
	ds_read_b64_tr_b16 v[190:191], v14 offset:26368
	v_mfma_f32_16x16x32_bf16 v[20:23], v[6:9], v[164:167], v[20:23]
	ds_read_b64_tr_b16 v[160:161], v14 offset:2048
	v_mfma_f32_16x16x32_bf16 v[84:87], v[152:155], v[164:167], v[84:87]
	ds_read_b64_tr_b16 v[162:163], v14 offset:10240
	s_waitcnt lgkmcnt(10)
	v_mfma_f32_16x16x32_bf16 v[24:27], v[6:9], v[168:171], v[24:27]
	ds_read_b64_tr_b16 v[164:165], v14 offset:18432
	v_mfma_f32_16x16x32_bf16 v[88:91], v[152:155], v[168:171], v[88:91]
	ds_read_b64_tr_b16 v[166:167], v14 offset:26624
	v_mfma_f32_16x16x32_bf16 v[28:31], v[6:9], v[172:175], v[28:31]
	ds_read_b64_tr_b16 v[168:169], v14 offset:2304
	v_mfma_f32_16x16x32_bf16 v[92:95], v[152:155], v[172:175], v[92:95]
	ds_read_b64_tr_b16 v[170:171], v14 offset:10496
	s_waitcnt lgkmcnt(10)
	v_mfma_f32_16x16x32_bf16 v[32:35], v[6:9], v[176:179], v[32:35]
	ds_read_b64_tr_b16 v[172:173], v14 offset:18688
	v_mfma_f32_16x16x32_bf16 v[96:99], v[152:155], v[176:179], v[96:99]
	ds_read_b64_tr_b16 v[174:175], v14 offset:26880
	v_mfma_f32_16x16x32_bf16 v[36:39], v[6:9], v[180:183], v[36:39]
	ds_read_b64_tr_b16 v[176:177], v14 offset:2560
	v_mfma_f32_16x16x32_bf16 v[100:103], v[152:155], v[180:183], v[100:103]
	ds_read_b64_tr_b16 v[178:179], v14 offset:10752
	s_waitcnt lgkmcnt(10)
	v_mfma_f32_16x16x32_bf16 v[40:43], v[6:9], v[184:187], v[40:43]
	ds_read_b64_tr_b16 v[180:181], v14 offset:18944
	v_mfma_f32_16x16x32_bf16 v[104:107], v[152:155], v[184:187], v[104:107]
	ds_read_b64_tr_b16 v[182:183], v14 offset:27136
	v_mfma_f32_16x16x32_bf16 v[44:47], v[6:9], v[188:191], v[44:47]
	ds_read_b64_tr_b16 v[184:185], v14 offset:2816
	v_mfma_f32_16x16x32_bf16 v[108:111], v[152:155], v[188:191], v[108:111]
	ds_read_b64_tr_b16 v[186:187], v14 offset:11008
	s_waitcnt lgkmcnt(10)
	v_mfma_f32_16x16x32_bf16 v[48:51], v[2:5], v[160:163], v[48:51]
	ds_read_b64_tr_b16 v[188:189], v14 offset:19200
	v_mfma_f32_16x16x32_bf16 v[112:115], v[10:13], v[160:163], v[112:115]
	ds_read_b64_tr_b16 v[190:191], v14 offset:27392
	v_mfma_f32_16x16x32_bf16 v[48:51], v[6:9], v[164:167], v[48:51]
	ds_read_b64_tr_b16 v[160:161], v14 offset:3072
	v_mfma_f32_16x16x32_bf16 v[112:115], v[152:155], v[164:167], v[112:115]
	ds_read_b64_tr_b16 v[162:163], v14 offset:11264
	s_waitcnt lgkmcnt(10)
	v_mfma_f32_16x16x32_bf16 v[52:55], v[2:5], v[168:171], v[52:55]
	ds_read_b64_tr_b16 v[164:165], v14 offset:19456
	v_mfma_f32_16x16x32_bf16 v[116:119], v[10:13], v[168:171], v[116:119]
	ds_read_b64_tr_b16 v[166:167], v14 offset:27648
	v_mfma_f32_16x16x32_bf16 v[52:55], v[6:9], v[172:175], v[52:55]
	ds_read_b64_tr_b16 v[168:169], v14 offset:3328
	v_mfma_f32_16x16x32_bf16 v[116:119], v[152:155], v[172:175], v[116:119]
	ds_read_b64_tr_b16 v[170:171], v14 offset:11520
	s_waitcnt lgkmcnt(10)
	v_mfma_f32_16x16x32_bf16 v[56:59], v[2:5], v[176:179], v[56:59]
	ds_read_b64_tr_b16 v[172:173], v14 offset:19712
	v_mfma_f32_16x16x32_bf16 v[120:123], v[10:13], v[176:179], v[120:123]
	ds_read_b64_tr_b16 v[174:175], v14 offset:27904
	v_mfma_f32_16x16x32_bf16 v[56:59], v[6:9], v[180:183], v[56:59]
	ds_read_b64_tr_b16 v[176:177], v14 offset:3584
	v_mfma_f32_16x16x32_bf16 v[120:123], v[152:155], v[180:183], v[120:123]
	ds_read_b64_tr_b16 v[178:179], v14 offset:11776
	s_waitcnt lgkmcnt(10)
	v_mfma_f32_16x16x32_bf16 v[60:63], v[2:5], v[184:187], v[60:63]
	ds_read_b64_tr_b16 v[180:181], v14 offset:19968
	v_mfma_f32_16x16x32_bf16 v[124:127], v[10:13], v[184:187], v[124:127]
	ds_read_b64_tr_b16 v[182:183], v14 offset:28160
	v_mfma_f32_16x16x32_bf16 v[60:63], v[6:9], v[188:191], v[60:63]
	ds_read_b64_tr_b16 v[184:185], v14 offset:3840
	v_mfma_f32_16x16x32_bf16 v[124:127], v[152:155], v[188:191], v[124:127]
	ds_read_b64_tr_b16 v[186:187], v14 offset:12032
	s_waitcnt lgkmcnt(10)
; #define SBAR() __builtin_amdgcn_sched_barrier(0)
; #define KM(d0, B0, B1) do { p0 = __builtin_amdgcn_mfma_f32_32x32x16_bf16(B0, qr[d0], p0, 0, 0, 0); p1 = __builtin_amdgcn_mfma_f32_32x32x16_bf16(B1, qr[d0], p1, 0, 0, 0); } while (0)
; #define HBAR(n) do { asm volatile("s_waitcnt vmcnt(" #n ") lgkmcnt(0)" ::: "memory"); __builtin_amdgcn_s_barrier(); asm volatile("" ::: "memory"); } while (0)
; #define LW(n) do { asm volatile("s_waitcnt lgkmcnt(" #n ")" ::: "memory"); SBAR(); } while (0)
; #define MF(S, k, D0, PA) do { o[D0] = __builtin_amdgcn_mfma_f32_32x32x16_bf16(PA, PKF(S##l##k, S##h##k), o[D0], 0, 0, 0); } while (0)
; #define LW(n) do { asm volatile("s_waitcnt lgkmcnt(" #n ")" ::: "memory"); SBAR(); } while (0)
; __device__ __forceinline__ void attn_dense_body(const bf16_t* __restrict__ Qb, const bf16_t* __restrict__ Kh, const bf16_t* __restrict__ Vh,
;                                                 float* __restrict__ Ob, int seq, char* lds, LAS unsigned char* lds3, const int tid) {
;     ...
;           PVB(A, B, 0, 1); PVB(B, A, 1, 2); PVB(A, B, 2, 3); PVB(B, A, 3, 4); PVB(A, B, 4, 5); PVB(B, A, 5, 6); PVB(A, B, 6, 7);
;           const int kadr = (int)(uintptr_t)K_lds + b1 * (int)SHM_K + r32 * 256; int kt = (hi * 16) ^ ((r32 & 7) << 4);
;           asm volatile("" : "+v"(kt));
;           bf16x8 k0a, k0b, k1a, k1b, k2a, k2b;
;     ...
;           LW(6); MF(B, 0, 7, pa0); SBAR(); KRD(0, k0a, k0b);
;           LW(6); MF(B, 1, 7, pa1); SBAR(); KRD(1, k1a, k1b);
;           LW(6); MF(B, 2, 7, pa2); SBAR(); KRD(2, k2a, k2b);
;           LW(6); MF(B, 3, 7, pa3); SBAR();
;           LW(4); p0 = __builtin_amdgcn_mfma_f32_32x32x16_bf16(k0a, qr[0], nm, 0, 0, 0); p1 = __builtin_amdgcn_mfma_f32_32x32x16_bf16(k0b, qr[0], nm, 0, 0, 0); SBAR(); KRD(3, k0a, k0b);
;           LW(4); KM(1, k1a, k1b); SBAR(); KRD(4, k1a, k1b);
;           LW(4); KM(2, k2a, k2b); SBAR(); KRD(5, k2a, k2b);
;           LW(4); KM(3, k0a, k0b); SBAR(); KRD(6, k0a, k0b);
;           LW(4); KM(4, k1a, k1b); SBAR(); KRD(7, k1a, k1b);
;           LW(4); KM(5, k2a, k2b); SBAR();
;           LW(2); KM(6, k0a, k0b); SBAR();
;           LW(0); KM(7, k1a, k1b);
;           __builtin_amdgcn_s_setprio(0);
;     ...
;         }
;     ...
;         HBAR(0);
;         { const int t_ = b; b = b1; b1 = b2; b2 = t_; }
;     }
	v_mfma_f32_16x16x32_bf16 v[64:67], v[2:5], v[160:163], v[64:67]
	ds_read_b64_tr_b16 v[188:189], v14 offset:20224
	v_mfma_f32_16x16x32_bf16 v[128:131], v[10:13], v[160:163], v[128:131]
	ds_read_b64_tr_b16 v[190:191], v14 offset:28416
	v_mfma_f32_16x16x32_bf16 v[64:67], v[6:9], v[164:167], v[64:67]
	v_mfma_f32_16x16x32_bf16 v[128:131], v[152:155], v[164:167], v[128:131]
	s_waitcnt lgkmcnt(8)
	v_mfma_f32_16x16x32_bf16 v[68:71], v[2:5], v[168:171], v[68:71]
	v_mfma_f32_16x16x32_bf16 v[132:135], v[10:13], v[168:171], v[132:135]
	v_mfma_f32_16x16x32_bf16 v[68:71], v[6:9], v[172:175], v[68:71]
	v_mfma_f32_16x16x32_bf16 v[132:135], v[152:155], v[172:175], v[132:135]
	s_waitcnt lgkmcnt(4)
	v_mfma_f32_16x16x32_bf16 v[72:75], v[2:5], v[176:179], v[72:75]
	v_mfma_f32_16x16x32_bf16 v[136:139], v[10:13], v[176:179], v[136:139]
	ds_read_b128 v[156:159], v0 offset:0
	v_mfma_f32_16x16x32_bf16 v[72:75], v[6:9], v[180:183], v[72:75]
	v_mfma_f32_16x16x32_bf16 v[136:139], v[152:155], v[180:183], v[136:139]
	ds_read_b128 v[224:227], v15 offset:0
	s_waitcnt lgkmcnt(2)
	v_mfma_f32_16x16x32_bf16 v[76:79], v[2:5], v[184:187], v[76:79]
	v_mfma_f32_16x16x32_bf16 v[140:143], v[10:13], v[184:187], v[140:143]
	ds_read_b128 v[234:237], v231 offset:0
	v_mfma_f32_16x16x32_bf16 v[76:79], v[6:9], v[188:191], v[76:79]
	v_mfma_f32_16x16x32_bf16 v[140:143], v[152:155], v[188:191], v[140:143]
	ds_read_b128 v[248:251], v232 offset:0
	ds_read_b128 v[2:5], v0 offset:4096
	ds_read_b128 v[6:9], v15 offset:4096
	ds_read_b128 v[10:13], v231 offset:4096
	ds_read_b128 v[152:155], v232 offset:4096
	s_waitcnt lgkmcnt(7)
	v_mfma_f32_16x16x32_bf16 v[160:163], v[156:159], v[192:195], v[144:147]
	v_mfma_f32_16x16x32_bf16 v[164:167], v[156:159], v[208:211], v[148:151]
	ds_read_b128 v[156:159], v0 offset:8192
	s_waitcnt lgkmcnt(7)
	v_mfma_f32_16x16x32_bf16 v[160:163], v[224:227], v[196:199], v[160:163]
	v_mfma_f32_16x16x32_bf16 v[164:167], v[224:227], v[212:215], v[164:167]
	ds_read_b128 v[224:227], v15 offset:8192
	s_waitcnt lgkmcnt(7)
	v_mfma_f32_16x16x32_bf16 v[160:163], v[234:237], v[200:203], v[160:163]
	v_mfma_f32_16x16x32_bf16 v[164:167], v[234:237], v[216:219], v[164:167]
	ds_read_b128 v[234:237], v231 offset:8192
	s_waitcnt lgkmcnt(7)
	v_mfma_f32_16x16x32_bf16 v[160:163], v[248:251], v[204:207], v[160:163]
	v_mfma_f32_16x16x32_bf16 v[164:167], v[248:251], v[220:223], v[164:167]
	ds_read_b128 v[248:251], v232 offset:8192
	s_waitcnt lgkmcnt(7)
	v_mfma_f32_16x16x32_bf16 v[168:171], v[2:5], v[192:195], v[144:147]
	v_mfma_f32_16x16x32_bf16 v[172:175], v[2:5], v[208:211], v[148:151]
	ds_read_b128 v[2:5], v0 offset:12288
	s_waitcnt lgkmcnt(7)
	v_mfma_f32_16x16x32_bf16 v[168:171], v[6:9], v[196:199], v[168:171]
	v_mfma_f32_16x16x32_bf16 v[172:175], v[6:9], v[212:215], v[172:175]
	ds_read_b128 v[6:9], v15 offset:12288
	s_waitcnt lgkmcnt(7)
	v_mfma_f32_16x16x32_bf16 v[168:171], v[10:13], v[200:203], v[168:171]
	v_mfma_f32_16x16x32_bf16 v[172:175], v[10:13], v[216:219], v[172:175]
	ds_read_b128 v[10:13], v231 offset:12288
	s_waitcnt lgkmcnt(7)
	v_mfma_f32_16x16x32_bf16 v[168:171], v[152:155], v[204:207], v[168:171]
	v_mfma_f32_16x16x32_bf16 v[172:175], v[152:155], v[220:223], v[172:175]
	ds_read_b128 v[152:155], v232 offset:12288
	s_waitcnt lgkmcnt(7)
	v_mfma_f32_16x16x32_bf16 v[176:179], v[156:159], v[192:195], v[144:147]
	v_mfma_f32_16x16x32_bf16 v[180:183], v[156:159], v[208:211], v[148:151]
	s_waitcnt lgkmcnt(6)
	v_mfma_f32_16x16x32_bf16 v[176:179], v[224:227], v[196:199], v[176:179]
	v_mfma_f32_16x16x32_bf16 v[180:183], v[224:227], v[212:215], v[180:183]
	s_waitcnt lgkmcnt(5)
	v_mfma_f32_16x16x32_bf16 v[176:179], v[234:237], v[200:203], v[176:179]
	v_mfma_f32_16x16x32_bf16 v[180:183], v[234:237], v[216:219], v[180:183]
	s_waitcnt lgkmcnt(4)
	v_mfma_f32_16x16x32_bf16 v[176:179], v[248:251], v[204:207], v[176:179]
	v_mfma_f32_16x16x32_bf16 v[180:183], v[248:251], v[220:223], v[180:183]
	s_waitcnt lgkmcnt(3)
	v_mfma_f32_16x16x32_bf16 v[184:187], v[2:5], v[192:195], v[144:147]
	v_mfma_f32_16x16x32_bf16 v[188:191], v[2:5], v[208:211], v[148:151]
	s_waitcnt lgkmcnt(2)
	v_mfma_f32_16x16x32_bf16 v[184:187], v[6:9], v[196:199], v[184:187]
	v_mfma_f32_16x16x32_bf16 v[188:191], v[6:9], v[212:215], v[188:191]
	s_waitcnt lgkmcnt(1)
	v_mfma_f32_16x16x32_bf16 v[184:187], v[10:13], v[200:203], v[184:187]
	v_mfma_f32_16x16x32_bf16 v[188:191], v[10:13], v[216:219], v[188:191]
	s_waitcnt lgkmcnt(0)
	v_mfma_f32_16x16x32_bf16 v[184:187], v[152:155], v[204:207], v[184:187]
	v_mfma_f32_16x16x32_bf16 v[188:191], v[152:155], v[220:223], v[188:191]
	s_setprio 0
	s_waitcnt vmcnt(0) lgkmcnt(0)
	s_barrier
	s_cmp_eq_u32 s15, s89
	s_cbranch_scc1 .Lat_done
	s_mov_b32 s0, s99
	s_mov_b32 s99, s10
	s_mov_b32 s10, s91
	s_branch .Lat_loop
; #define SBAR() __builtin_amdgcn_sched_barrier(0)
; #define KM(d0, B0, B1) do { p0 = __builtin_amdgcn_mfma_f32_32x32x16_bf16(B0, qr[d0], p0, 0, 0, 0); p1 = __builtin_amdgcn_mfma_f32_32x32x16_bf16(B1, qr[d0], p1, 0, 0, 0); } while (0)
; #define LW(n) do { asm volatile("s_waitcnt lgkmcnt(" #n ")" ::: "memory"); SBAR(); } while (0)
; #define MF(S, k, D0, PA) do { o[D0] = __builtin_amdgcn_mfma_f32_32x32x16_bf16(PA, PKF(S##l##k, S##h##k), o[D0], 0, 0, 0); } while (0)
; #define LW(n) do { asm volatile("s_waitcnt lgkmcnt(" #n ")" ::: "memory"); SBAR(); } while (0)
; #define KRD(d0, RA, RB) do { const int ad_ = kadr + (kt ^ ((d0) * 32)); asm volatile("ds_read_b128 %0, %1" : "=&v"(RA) : "v"(ad_) : "memory"); \
;     asm volatile("ds_read_b128 %0, %1 offset:8192" : "=&v"(RB) : "v"(ad_) : "memory"); } while (0)
; #define KM(d0, RA, RB) do { p0 = __builtin_amdgcn_mfma_f32_32x32x16_bf16(RA, qr[d0], p0, 0, 0, 0); p1 = __builtin_amdgcn_mfma_f32_32x32x16_bf16(RB, qr[d0], p1, 0, 0, 0); } while (0)
; __device__ __forceinline__ void attn_dense_body(const bf16_t* __restrict__ Qb, const bf16_t* __restrict__ Kh, const bf16_t* __restrict__ Vh,
;                                                 float* __restrict__ Ob, int seq, char* lds, LAS unsigned char* lds3, const int tid) {
;     ...
;           const int kadr = (int)(uintptr_t)K_lds + b1 * (int)SHM_K + r32 * 256; int kt = (hi * 16) ^ ((r32 & 7) << 4);
;           asm volatile("" : "+v"(kt));
;           bf16x8 k0a, k0b, k1a, k1b, k2a, k2b;
;     ...
;           LW(6); MF(B, 0, 7, pa0); SBAR(); KRD(0, k0a, k0b);
;           LW(6); MF(B, 1, 7, pa1); SBAR(); KRD(1, k1a, k1b);
;           LW(6); MF(B, 2, 7, pa2); SBAR(); KRD(2, k2a, k2b);
;           LW(6); MF(B, 3, 7, pa3); SBAR();
;           LW(4); p0 = __builtin_amdgcn_mfma_f32_32x32x16_bf16(k0a, qr[0], nm, 0, 0, 0); p1 = __builtin_amdgcn_mfma_f32_32x32x16_bf16(k0b, qr[0], nm, 0, 0, 0); SBAR(); KRD(3, k0a, k0b);
;           LW(4); KM(1, k1a, k1b); SBAR(); KRD(4, k1a, k1b);
;           LW(4); KM(2, k2a, k2b); SBAR(); KRD(5, k2a, k2b);
;           LW(4); KM(3, k0a, k0b); SBAR(); KRD(6, k0a, k0b);
;           LW(4); KM(4, k1a, k1b); SBAR(); KRD(7, k1a, k1b);
;           LW(4); KM(5, k2a, k2b); SBAR();
;           LW(2); KM(6, k0a, k0b); SBAR();
;           LW(0); KM(7, k1a, k1b);
.Lat_redo:
	v_lshl_add_u32 v232, s91, 14, v246
	v_add_u32_e32 v0, v239, v232
	v_xad_u32 v15, v239, 64, v232
	v_xad_u32 v231, v239, s60, v232
	s_movk_i32 s0, 0xc0
	v_xad_u32 v232, v239, s0, v232
	ds_read_b128 v[156:159], v0 offset:0
	ds_read_b128 v[224:227], v15 offset:0
	ds_read_b128 v[234:237], v231 offset:0
	ds_read_b128 v[248:251], v232 offset:0
	s_waitcnt lgkmcnt(3)
	v_mfma_f32_16x16x32_bf16 v[160:163], v[156:159], v[192:195], v[144:147]
	v_mfma_f32_16x16x32_bf16 v[164:167], v[156:159], v[208:211], v[148:151]
	ds_read_b128 v[156:159], v0 offset:4096
	s_waitcnt lgkmcnt(3)
	v_mfma_f32_16x16x32_bf16 v[160:163], v[224:227], v[196:199], v[160:163]
	v_mfma_f32_16x16x32_bf16 v[164:167], v[224:227], v[212:215], v[164:167]
	ds_read_b128 v[224:227], v15 offset:4096
	s_waitcnt lgkmcnt(3)
	v_mfma_f32_16x16x32_bf16 v[160:163], v[234:237], v[200:203], v[160:163]
	v_mfma_f32_16x16x32_bf16 v[164:167], v[234:237], v[216:219], v[164:167]
	ds_read_b128 v[234:237], v231 offset:4096
	s_waitcnt lgkmcnt(3)
	v_mfma_f32_16x16x32_bf16 v[160:163], v[248:251], v[204:207], v[160:163]
	v_mfma_f32_16x16x32_bf16 v[164:167], v[248:251], v[220:223], v[164:167]
	ds_read_b128 v[248:251], v232 offset:4096
	s_waitcnt lgkmcnt(3)
	v_mfma_f32_16x16x32_bf16 v[168:171], v[156:159], v[192:195], v[144:147]
	v_mfma_f32_16x16x32_bf16 v[172:175], v[156:159], v[208:211], v[148:151]
	ds_read_b128 v[156:159], v0 offset:8192
	s_waitcnt lgkmcnt(3)
	v_mfma_f32_16x16x32_bf16 v[168:171], v[224:227], v[196:199], v[168:171]
	v_mfma_f32_16x16x32_bf16 v[172:175], v[224:227], v[212:215], v[172:175]
	ds_read_b128 v[224:227], v15 offset:8192
	s_waitcnt lgkmcnt(3)
	v_mfma_f32_16x16x32_bf16 v[168:171], v[234:237], v[200:203], v[168:171]
	v_mfma_f32_16x16x32_bf16 v[172:175], v[234:237], v[216:219], v[172:175]
	ds_read_b128 v[234:237], v231 offset:8192
	s_waitcnt lgkmcnt(3)
	v_mfma_f32_16x16x32_bf16 v[168:171], v[248:251], v[204:207], v[168:171]
	v_mfma_f32_16x16x32_bf16 v[172:175], v[248:251], v[220:223], v[172:175]
	ds_read_b128 v[248:251], v232 offset:8192
	s_waitcnt lgkmcnt(3)
	v_mfma_f32_16x16x32_bf16 v[176:179], v[156:159], v[192:195], v[144:147]
	v_mfma_f32_16x16x32_bf16 v[180:183], v[156:159], v[208:211], v[148:151]
	ds_read_b128 v[156:159], v0 offset:12288
	s_waitcnt lgkmcnt(3)
	v_mfma_f32_16x16x32_bf16 v[176:179], v[224:227], v[196:199], v[176:179]
	v_mfma_f32_16x16x32_bf16 v[180:183], v[224:227], v[212:215], v[180:183]
	ds_read_b128 v[224:227], v15 offset:12288
	s_waitcnt lgkmcnt(3)
	v_mfma_f32_16x16x32_bf16 v[176:179], v[234:237], v[200:203], v[176:179]
	v_mfma_f32_16x16x32_bf16 v[180:183], v[234:237], v[216:219], v[180:183]
	ds_read_b128 v[234:237], v231 offset:12288
	s_waitcnt lgkmcnt(3)
	v_mfma_f32_16x16x32_bf16 v[176:179], v[248:251], v[204:207], v[176:179]
	v_mfma_f32_16x16x32_bf16 v[180:183], v[248:251], v[220:223], v[180:183]
	ds_read_b128 v[248:251], v232 offset:12288
	s_waitcnt lgkmcnt(3)
	v_mfma_f32_16x16x32_bf16 v[184:187], v[156:159], v[192:195], v[144:147]
	v_mfma_f32_16x16x32_bf16 v[188:191], v[156:159], v[208:211], v[148:151]
	s_waitcnt lgkmcnt(2)
	v_mfma_f32_16x16x32_bf16 v[184:187], v[224:227], v[196:199], v[184:187]
	v_mfma_f32_16x16x32_bf16 v[188:191], v[224:227], v[212:215], v[188:191]
	s_waitcnt lgkmcnt(1)
	v_mfma_f32_16x16x32_bf16 v[184:187], v[234:237], v[200:203], v[184:187]
	v_mfma_f32_16x16x32_bf16 v[188:191], v[234:237], v[216:219], v[188:191]
	s_waitcnt lgkmcnt(0)
	v_mfma_f32_16x16x32_bf16 v[184:187], v[248:251], v[204:207], v[184:187]
	v_mfma_f32_16x16x32_bf16 v[188:191], v[248:251], v[220:223], v[188:191]
	s_nop 7
	s_nop 1
; __device__ __forceinline__ void partialSM(f32x16& p0, f32x16& p1, f32x16& nm, bool first, float& alpha) {
;     float pmax = p0[0]; for (int r = 1; r < 16; ++r) pmax = fmaxf(pmax, p0[r]); for (int r = 0; r < 16; ++r) pmax = fmaxf(pmax, p1[r]);
;     { auto rr = __builtin_amdgcn_permlane32_swap(__float_as_uint(pmax), __float_as_uint(pmax), false, false);
;       pmax = fmaxf(__uint_as_float(rr[0]), __uint_as_float(rr[1])); }
;     if (__builtin_expect(!first && __all(pmax <= THRL), 1)) { alpha = 1.f; }
;     else {
;         const float delta = first ? pmax : fmaxf(pmax, 0.f);
;         alpha = first ? 1.f : __builtin_amdgcn_exp2f(-delta);
;         for (int r = 0; r < 16; ++r) { p0[r] -= delta; p1[r] -= delta; nm[r] -= delta; }
;     }
.Lat_resc:
	s_mov_b32 s84, 1
	s_cmp_eq_u32 s1, 0
	s_cselect_b64 s[18:19], -1, 0
	v_max3_f32 v0, v160, v161, v162
	v_max3_f32 v0, v0, v163, v168
	v_max3_f32 v0, v0, v169, v170
	v_max3_f32 v0, v0, v171, v176
	v_max3_f32 v0, v0, v177, v178
	v_max3_f32 v0, v0, v179, v184
	v_max3_f32 v0, v0, v185, v186
	v_max_f32_e32 v0, v0, v187
	v_max3_f32 v14, v164, v165, v166
	v_max3_f32 v14, v14, v167, v172
	v_max3_f32 v14, v14, v173, v174
	v_max3_f32 v14, v14, v175, v180
	v_max3_f32 v14, v14, v181, v182
	v_max3_f32 v14, v14, v183, v188
	v_max3_f32 v14, v14, v189, v190
	v_max_f32_e32 v14, v14, v191
	v_mov_b32_e32 v15, v0
	s_nop 1
	v_permlane16_swap_b32_e32 v0, v15
	v_max_f32_e32 v0, v0, v15
	v_mov_b32_e32 v15, v0
	s_nop 1
	v_permlane32_swap_b32_e32 v0, v15
	v_max_f32_e32 v0, v0, v15
	v_mov_b32_e32 v15, v14
	s_nop 1
	v_permlane16_swap_b32_e32 v14, v15
	v_max_f32_e32 v14, v14, v15
	v_mov_b32_e32 v15, v14
	s_nop 1
	v_permlane32_swap_b32_e32 v14, v15
	v_max_f32_e32 v14, v14, v15
	v_max_f32_e32 v15, 0, v0
	v_max_f32_e32 v224, 0, v14
	s_nop 0
	v_cndmask_b32_e64 v0, v15, v0, s[18:19]
	v_cndmask_b32_e64 v14, v224, v14, s[18:19]
	v_exp_f32_e64 v224, -v0
	v_exp_f32_e64 v225, -v14
	s_nop 0
	v_cndmask_b32_e64 v224, v224, 1.0, s[18:19]
	v_cndmask_b32_e64 v225, v225, 1.0, s[18:19]
	v_sub_f32_e32 v160, v160, v0
	v_sub_f32_e32 v161, v161, v0
	v_sub_f32_e32 v162, v162, v0
	v_sub_f32_e32 v163, v163, v0
	v_sub_f32_e32 v168, v168, v0
	v_sub_f32_e32 v169, v169, v0
	v_sub_f32_e32 v170, v170, v0
	v_sub_f32_e32 v171, v171, v0
	v_sub_f32_e32 v176, v176, v0
	v_sub_f32_e32 v177, v177, v0
	v_sub_f32_e32 v178, v178, v0
	v_sub_f32_e32 v179, v179, v0
	v_sub_f32_e32 v184, v184, v0
	v_sub_f32_e32 v185, v185, v0
	v_sub_f32_e32 v186, v186, v0
	v_sub_f32_e32 v187, v187, v0
	v_sub_f32_e32 v164, v164, v14
	v_sub_f32_e32 v165, v165, v14
	v_sub_f32_e32 v166, v166, v14
	v_sub_f32_e32 v167, v167, v14
	v_sub_f32_e32 v172, v172, v14
	v_sub_f32_e32 v173, v173, v14
	v_sub_f32_e32 v174, v174, v14
	v_sub_f32_e32 v175, v175, v14
	v_sub_f32_e32 v180, v180, v14
	v_sub_f32_e32 v181, v181, v14
	v_sub_f32_e32 v182, v182, v14
	v_sub_f32_e32 v183, v183, v14
	v_sub_f32_e32 v188, v188, v14
	v_sub_f32_e32 v189, v189, v14
	v_sub_f32_e32 v190, v190, v14
	v_sub_f32_e32 v191, v191, v14
	v_sub_f32_e32 v144, v144, v0
	v_sub_f32_e32 v145, v145, v0
	v_sub_f32_e32 v146, v146, v0
	v_sub_f32_e32 v147, v147, v0
	v_sub_f32_e32 v148, v148, v14
	v_sub_f32_e32 v149, v149, v14
	v_sub_f32_e32 v150, v150, v14
	v_sub_f32_e32 v151, v151, v14
	v_mul_f32_e32 v245, v245, v224
	v_mul_f32_e32 v229, v229, v225
	v_min_f32_e32 v15, v224, v225
	v_cmp_gt_f32_e32 vcc, 1.0, v15
	s_cbranch_vccz .Lat_exp
	v_mbcnt_lo_u32_b32 v248, -1, 0
	v_mbcnt_hi_u32_b32 v248, -1, v248
	v_and_b32_e32 v249, 15, v248
	v_lshrrev_b32_e32 v248, 4, v248
	v_lshl_add_u32 v249, v249, 2, v243
	v_lshl_add_u32 v248, v248, 4, v243
	ds_write_b32 v249, v224 offset:128
	ds_write_b32 v249, v225 offset:192
	s_waitcnt lgkmcnt(0)
	ds_read_b128 v[156:159], v248 offset:128
	ds_read_b128 v[234:237], v248 offset:192
	s_waitcnt lgkmcnt(0)
	v_pk_mul_f32 v[16:17], v[16:17], v[156:157]
	v_pk_mul_f32 v[18:19], v[18:19], v[158:159]
	v_pk_mul_f32 v[20:21], v[20:21], v[156:157]
	v_pk_mul_f32 v[22:23], v[22:23], v[158:159]
	v_pk_mul_f32 v[24:25], v[24:25], v[156:157]
	v_pk_mul_f32 v[26:27], v[26:27], v[158:159]
	v_pk_mul_f32 v[28:29], v[28:29], v[156:157]
	v_pk_mul_f32 v[30:31], v[30:31], v[158:159]
	v_pk_mul_f32 v[32:33], v[32:33], v[156:157]
	v_pk_mul_f32 v[34:35], v[34:35], v[158:159]
	v_pk_mul_f32 v[36:37], v[36:37], v[156:157]
	v_pk_mul_f32 v[38:39], v[38:39], v[158:159]
	v_pk_mul_f32 v[40:41], v[40:41], v[156:157]
	v_pk_mul_f32 v[42:43], v[42:43], v[158:159]
	v_pk_mul_f32 v[44:45], v[44:45], v[156:157]
	v_pk_mul_f32 v[46:47], v[46:47], v[158:159]
	v_pk_mul_f32 v[48:49], v[48:49], v[156:157]
	v_pk_mul_f32 v[50:51], v[50:51], v[158:159]
	v_pk_mul_f32 v[52:53], v[52:53], v[156:157]
	v_pk_mul_f32 v[54:55], v[54:55], v[158:159]
	v_pk_mul_f32 v[56:57], v[56:57], v[156:157]
	v_pk_mul_f32 v[58:59], v[58:59], v[158:159]
	v_pk_mul_f32 v[60:61], v[60:61], v[156:157]
	v_pk_mul_f32 v[62:63], v[62:63], v[158:159]
	v_pk_mul_f32 v[64:65], v[64:65], v[156:157]
	v_pk_mul_f32 v[66:67], v[66:67], v[158:159]
	v_pk_mul_f32 v[68:69], v[68:69], v[156:157]
	v_pk_mul_f32 v[70:71], v[70:71], v[158:159]
	v_pk_mul_f32 v[72:73], v[72:73], v[156:157]
	v_pk_mul_f32 v[74:75], v[74:75], v[158:159]
	v_pk_mul_f32 v[76:77], v[76:77], v[156:157]
	v_pk_mul_f32 v[78:79], v[78:79], v[158:159]
	v_pk_mul_f32 v[80:81], v[80:81], v[234:235]
	v_pk_mul_f32 v[82:83], v[82:83], v[236:237]
	v_pk_mul_f32 v[84:85], v[84:85], v[234:235]
	v_pk_mul_f32 v[86:87], v[86:87], v[236:237]
	v_pk_mul_f32 v[88:89], v[88:89], v[234:235]
	v_pk_mul_f32 v[90:91], v[90:91], v[236:237]
	v_pk_mul_f32 v[92:93], v[92:93], v[234:235]
	v_pk_mul_f32 v[94:95], v[94:95], v[236:237]
	v_pk_mul_f32 v[96:97], v[96:97], v[234:235]
	v_pk_mul_f32 v[98:99], v[98:99], v[236:237]
	v_pk_mul_f32 v[100:101], v[100:101], v[234:235]
	v_pk_mul_f32 v[102:103], v[102:103], v[236:237]
	v_pk_mul_f32 v[104:105], v[104:105], v[234:235]
	v_pk_mul_f32 v[106:107], v[106:107], v[236:237]
	v_pk_mul_f32 v[108:109], v[108:109], v[234:235]
	v_pk_mul_f32 v[110:111], v[110:111], v[236:237]
	v_pk_mul_f32 v[112:113], v[112:113], v[234:235]
	v_pk_mul_f32 v[114:115], v[114:115], v[236:237]
	v_pk_mul_f32 v[116:117], v[116:117], v[234:235]
	v_pk_mul_f32 v[118:119], v[118:119], v[236:237]
	v_pk_mul_f32 v[120:121], v[120:121], v[234:235]
	v_pk_mul_f32 v[122:123], v[122:123], v[236:237]
	v_pk_mul_f32 v[124:125], v[124:125], v[234:235]
	v_pk_mul_f32 v[126:127], v[126:127], v[236:237]
	v_pk_mul_f32 v[128:129], v[128:129], v[234:235]
	v_pk_mul_f32 v[130:131], v[130:131], v[236:237]
	v_pk_mul_f32 v[132:133], v[132:133], v[234:235]
	v_pk_mul_f32 v[134:135], v[134:135], v[236:237]
	v_pk_mul_f32 v[136:137], v[136:137], v[234:235]
	v_pk_mul_f32 v[138:139], v[138:139], v[236:237]
	v_pk_mul_f32 v[140:141], v[140:141], v[234:235]
	v_pk_mul_f32 v[142:143], v[142:143], v[236:237]
	s_branch .Lat_exp
